# scan waves run their chunk body at s_setprio 3 (staging partner wave at 0)
# baseline (speedup 1.0000x reference)
.LBB0_1092:
	s_mov_b64 s[92:93], -1
	s_and_b64 vcc, exec, s[88:89]
	s_cbranch_vccz .LBB0_1098
	s_setprio 3
	s_bitcmp1_b32 s9, 0
	s_cselect_b32 s7, 0xb200, 0
	s_add_i32 s26, s7, 0
	s_mov_b64 s[82:83], s[96:97]
	s_mov_b32 s84, s80
	v_lshl_add_u32 v174, v102, 2, s26
	v_mov_b32_e32 v175, s26
	v_add_u32_e32 v163, s26, v160
	v_mov_b64_e32 v[144:145], v[140:141]
	v_mov_b64_e32 v[146:147], v[142:143]
	v_mov_b32_e32 v162, v111
	ds_read_b128 v[0:3], v174 offset:0
	ds_read_b128 v[4:7], v174 offset:256
	ds_read_b128 v[8:11], v174 offset:512
	ds_read_b128 v[12:15], v174 offset:768
	ds_read_b128 v[16:19], v174 offset:1024
	ds_read_b128 v[20:23], v174 offset:1280
	ds_read_b128 v[24:27], v174 offset:1536
	ds_read_b128 v[28:31], v174 offset:1792
	ds_read_b128 v[32:35], v174 offset:2048
	ds_read_b128 v[36:39], v175 offset:2816
	ds_read_b32 v40, v163 offset:2304
	ds_read_b32 v41, v163 offset:2560
	s_waitcnt lgkmcnt(0)
	v_pk_mul_f32 v[96:97], v[144:145], v[50:51]
	v_pk_mul_f32 v[98:99], v[144:145], v[0:1]
	v_pk_mul_f32 v[100:101], v[144:145], v[4:5]
	v_pk_mul_f32 v[172:173], v[144:145], v[8:9]
	v_pk_fma_f32 v[96:97], v[146:147], v[52:53], v[96:97]
	v_pk_fma_f32 v[98:99], v[146:147], v[2:3], v[98:99]
	v_pk_fma_f32 v[100:101], v[146:147], v[6:7], v[100:101]
	v_pk_fma_f32 v[172:173], v[146:147], v[10:11], v[172:173]
	ds_read_b128 v[54:57], v174 offset:2848
	ds_read_b128 v[58:61], v174 offset:3104
	ds_read_b128 v[62:65], v174 offset:3360
	ds_read_b128 v[66:69], v174 offset:3616
	ds_read_b128 v[70:73], v174 offset:3872
	ds_read_b128 v[74:77], v174 offset:4128
	ds_read_b128 v[78:81], v174 offset:4384
	ds_read_b128 v[82:85], v174 offset:4640
	ds_read_b128 v[86:89], v174 offset:4896
	ds_read_b128 v[90:93], v175 offset:5664
	ds_read_b32 v94, v163 offset:5152
	ds_read_b32 v95, v163 offset:5408
	v_pk_mul_f32 v[148:149], v[24:25], v[40:41] op_sel_hi:[1,0]
	v_pk_mul_f32 v[150:151], v[26:27], v[40:41] op_sel_hi:[1,0]
	v_add_f32_e32 v168, v96, v97
	v_add_f32_e32 v166, v98, v99
	v_add_f32_e32 v169, v100, v101
	v_add_f32_e32 v170, v172, v173
	v_pk_fma_f32 v[148:149], v[32:33], v[40:41], v[148:149] op_sel:[0,1,0] op_sel_hi:[1,1,1]
	v_pk_fma_f32 v[150:151], v[34:35], v[40:41], v[150:151] op_sel:[0,1,0] op_sel_hi:[1,1,1]
	v_add_f32_dpp v168, v168, v168 row_mirror row_mask:0xf bank_mask:0xf bound_ctrl:1
	v_add_f32_dpp v166, v166, v166 row_mirror row_mask:0xf bank_mask:0xf bound_ctrl:1
	v_add_f32_dpp v169, v169, v169 row_mirror row_mask:0xf bank_mask:0xf bound_ctrl:1
	v_add_f32_dpp v170, v170, v170 row_mirror row_mask:0xf bank_mask:0xf bound_ctrl:1
	v_add_f32_dpp v168, v168, v168 row_half_mirror row_mask:0xf bank_mask:0xf bound_ctrl:1
	v_add_f32_dpp v166, v166, v166 row_half_mirror row_mask:0xf bank_mask:0xf bound_ctrl:1
	v_add_f32_dpp v169, v169, v169 row_half_mirror row_mask:0xf bank_mask:0xf bound_ctrl:1
	v_add_f32_dpp v170, v170, v170 row_half_mirror row_mask:0xf bank_mask:0xf bound_ctrl:1
	v_add_f32_dpp v168, v168, v168 quad_perm:[1,0,3,2] row_mask:0xf bank_mask:0xf bound_ctrl:1
	v_add_f32_dpp v166, v166, v166 quad_perm:[1,0,3,2] row_mask:0xf bank_mask:0xf bound_ctrl:1
	v_add_f32_dpp v169, v169, v169 quad_perm:[1,0,3,2] row_mask:0xf bank_mask:0xf bound_ctrl:1
	v_add_f32_dpp v170, v170, v170 quad_perm:[1,0,3,2] row_mask:0xf bank_mask:0xf bound_ctrl:1
	v_add_f32_dpp v168, v168, v168 quad_perm:[2,3,0,1] row_mask:0xf bank_mask:0xf bound_ctrl:1
	v_add_f32_dpp v166, v166, v166 quad_perm:[2,3,0,1] row_mask:0xf bank_mask:0xf bound_ctrl:1
	v_add_f32_dpp v169, v169, v169 quad_perm:[2,3,0,1] row_mask:0xf bank_mask:0xf bound_ctrl:1
	v_add_f32_dpp v170, v170, v170 quad_perm:[2,3,0,1] row_mask:0xf bank_mask:0xf bound_ctrl:1
	v_fma_f32 v164, v40, v37, v169
	v_fma_f32 v171, v40, v39, v170
	v_pk_fma_f32 v[148:149], v[20:21], v[166:167], v[148:149] op_sel_hi:[1,0,1]
	v_fma_f32 v167, v166, v36, v164
	v_pk_fma_f32 v[150:151], v[22:23], v[166:167], v[150:151] op_sel_hi:[1,0,1]
	v_fma_f32 v171, v166, v38, v171
	v_cndmask_b32_e64 v162, v162, v168, s[46:47]
	s_lshl_b32 s6, s9, 1
	s_cmp_eq_u32 s6, 0
	s_cbranch_scc1 .Lscan_noy0
	s_add_i32 s6, s6, -1
	s_and_b32 s6, s6, 7
	s_lshl_b32 s6, s6, 10
	v_add_u32_e32 v161, s6, v156
	ds_write_b32 v161, v162
.Lscan_noy0:
	v_pk_fma_f32 v[148:149], v[28:29], v[166:167], v[148:149] op_sel:[0,1,0] op_sel_hi:[1,1,1]
	v_pk_fma_f32 v[150:151], v[30:31], v[166:167], v[150:151] op_sel:[0,1,0] op_sel_hi:[1,1,1]
	v_cndmask_b32_e64 v162, v162, v171, s[38:39]
	v_pk_fma_f32 v[144:145], v[144:145], v[16:17], v[148:149]
	v_pk_fma_f32 v[146:147], v[146:147], v[18:19], v[150:151]
	s_waitcnt lgkmcnt(0)
	v_pk_mul_f32 v[96:97], v[144:145], v[12:13]
	v_pk_mul_f32 v[98:99], v[144:145], v[54:55]
	v_pk_mul_f32 v[100:101], v[144:145], v[58:59]
	v_pk_mul_f32 v[172:173], v[144:145], v[62:63]
	v_pk_fma_f32 v[96:97], v[146:147], v[14:15], v[96:97]
	v_pk_fma_f32 v[98:99], v[146:147], v[56:57], v[98:99]
	v_pk_fma_f32 v[100:101], v[146:147], v[60:61], v[100:101]
	v_pk_fma_f32 v[172:173], v[146:147], v[64:65], v[172:173]
	ds_read_b128 v[0:3], v174 offset:5696
	ds_read_b128 v[4:7], v174 offset:5952
	ds_read_b128 v[8:11], v174 offset:6208
	ds_read_b128 v[12:15], v174 offset:6464
	ds_read_b128 v[16:19], v174 offset:6720
	ds_read_b128 v[20:23], v174 offset:6976
	ds_read_b128 v[24:27], v174 offset:7232
	ds_read_b128 v[28:31], v174 offset:7488
	ds_read_b128 v[32:35], v174 offset:7744
	ds_read_b128 v[36:39], v175 offset:8512
	ds_read_b32 v40, v163 offset:8000
	ds_read_b32 v41, v163 offset:8256
	v_pk_mul_f32 v[148:149], v[78:79], v[94:95] op_sel_hi:[1,0]
	v_pk_mul_f32 v[150:151], v[80:81], v[94:95] op_sel_hi:[1,0]
	v_add_f32_e32 v168, v96, v97
	v_add_f32_e32 v166, v98, v99
	v_add_f32_e32 v169, v100, v101
	v_add_f32_e32 v170, v172, v173
	v_pk_fma_f32 v[148:149], v[86:87], v[94:95], v[148:149] op_sel:[0,1,0] op_sel_hi:[1,1,1]
	v_pk_fma_f32 v[150:151], v[88:89], v[94:95], v[150:151] op_sel:[0,1,0] op_sel_hi:[1,1,1]
	v_add_f32_dpp v168, v168, v168 row_mirror row_mask:0xf bank_mask:0xf bound_ctrl:1
	v_add_f32_dpp v166, v166, v166 row_mirror row_mask:0xf bank_mask:0xf bound_ctrl:1
	v_add_f32_dpp v169, v169, v169 row_mirror row_mask:0xf bank_mask:0xf bound_ctrl:1
	v_add_f32_dpp v170, v170, v170 row_mirror row_mask:0xf bank_mask:0xf bound_ctrl:1
	v_add_f32_dpp v168, v168, v168 row_half_mirror row_mask:0xf bank_mask:0xf bound_ctrl:1
	v_add_f32_dpp v166, v166, v166 row_half_mirror row_mask:0xf bank_mask:0xf bound_ctrl:1
	v_add_f32_dpp v169, v169, v169 row_half_mirror row_mask:0xf bank_mask:0xf bound_ctrl:1
	v_add_f32_dpp v170, v170, v170 row_half_mirror row_mask:0xf bank_mask:0xf bound_ctrl:1
	v_add_f32_dpp v168, v168, v168 quad_perm:[1,0,3,2] row_mask:0xf bank_mask:0xf bound_ctrl:1
	v_add_f32_dpp v166, v166, v166 quad_perm:[1,0,3,2] row_mask:0xf bank_mask:0xf bound_ctrl:1
	v_add_f32_dpp v169, v169, v169 quad_perm:[1,0,3,2] row_mask:0xf bank_mask:0xf bound_ctrl:1
	v_add_f32_dpp v170, v170, v170 quad_perm:[1,0,3,2] row_mask:0xf bank_mask:0xf bound_ctrl:1
	v_add_f32_dpp v168, v168, v168 quad_perm:[2,3,0,1] row_mask:0xf bank_mask:0xf bound_ctrl:1
	v_add_f32_dpp v166, v166, v166 quad_perm:[2,3,0,1] row_mask:0xf bank_mask:0xf bound_ctrl:1
	v_add_f32_dpp v169, v169, v169 quad_perm:[2,3,0,1] row_mask:0xf bank_mask:0xf bound_ctrl:1
	v_add_f32_dpp v170, v170, v170 quad_perm:[2,3,0,1] row_mask:0xf bank_mask:0xf bound_ctrl:1
	v_fma_f32 v164, v94, v91, v169
	v_fma_f32 v171, v94, v93, v170
	v_pk_fma_f32 v[148:149], v[74:75], v[166:167], v[148:149] op_sel_hi:[1,0,1]
	v_fma_f32 v167, v166, v90, v164
	v_pk_fma_f32 v[150:151], v[76:77], v[166:167], v[150:151] op_sel_hi:[1,0,1]
	v_fma_f32 v171, v166, v92, v171
	v_cndmask_b32_e64 v162, v162, v168, s[48:49]
	v_pk_fma_f32 v[148:149], v[82:83], v[166:167], v[148:149] op_sel:[0,1,0] op_sel_hi:[1,1,1]
	v_pk_fma_f32 v[150:151], v[84:85], v[166:167], v[150:151] op_sel:[0,1,0] op_sel_hi:[1,1,1]
	v_cndmask_b32_e64 v162, v162, v171, s[50:51]
	v_pk_fma_f32 v[144:145], v[144:145], v[70:71], v[148:149]
	v_pk_fma_f32 v[146:147], v[146:147], v[72:73], v[150:151]
	s_waitcnt lgkmcnt(0)
	v_pk_mul_f32 v[96:97], v[144:145], v[66:67]
	v_pk_mul_f32 v[98:99], v[144:145], v[0:1]
	v_pk_mul_f32 v[100:101], v[144:145], v[4:5]
	v_pk_mul_f32 v[172:173], v[144:145], v[8:9]
	v_pk_fma_f32 v[96:97], v[146:147], v[68:69], v[96:97]
	v_pk_fma_f32 v[98:99], v[146:147], v[2:3], v[98:99]
	v_pk_fma_f32 v[100:101], v[146:147], v[6:7], v[100:101]
	v_pk_fma_f32 v[172:173], v[146:147], v[10:11], v[172:173]
	ds_read_b128 v[54:57], v174 offset:8544
	ds_read_b128 v[58:61], v174 offset:8800
	ds_read_b128 v[62:65], v174 offset:9056
	ds_read_b128 v[66:69], v174 offset:9312
	ds_read_b128 v[70:73], v174 offset:9568
	ds_read_b128 v[74:77], v174 offset:9824
	ds_read_b128 v[78:81], v174 offset:10080
	ds_read_b128 v[82:85], v174 offset:10336
	ds_read_b128 v[86:89], v174 offset:10592
	ds_read_b128 v[90:93], v175 offset:11360
	ds_read_b32 v94, v163 offset:10848
	ds_read_b32 v95, v163 offset:11104
	v_pk_mul_f32 v[148:149], v[24:25], v[40:41] op_sel_hi:[1,0]
	v_pk_mul_f32 v[150:151], v[26:27], v[40:41] op_sel_hi:[1,0]
	v_add_f32_e32 v168, v96, v97
	v_add_f32_e32 v166, v98, v99
	v_add_f32_e32 v169, v100, v101
	v_add_f32_e32 v170, v172, v173
	v_pk_fma_f32 v[148:149], v[32:33], v[40:41], v[148:149] op_sel:[0,1,0] op_sel_hi:[1,1,1]
	v_pk_fma_f32 v[150:151], v[34:35], v[40:41], v[150:151] op_sel:[0,1,0] op_sel_hi:[1,1,1]
	v_add_f32_dpp v168, v168, v168 row_mirror row_mask:0xf bank_mask:0xf bound_ctrl:1
	v_add_f32_dpp v166, v166, v166 row_mirror row_mask:0xf bank_mask:0xf bound_ctrl:1
	v_add_f32_dpp v169, v169, v169 row_mirror row_mask:0xf bank_mask:0xf bound_ctrl:1
	v_add_f32_dpp v170, v170, v170 row_mirror row_mask:0xf bank_mask:0xf bound_ctrl:1
	v_add_f32_dpp v168, v168, v168 row_half_mirror row_mask:0xf bank_mask:0xf bound_ctrl:1
	v_add_f32_dpp v166, v166, v166 row_half_mirror row_mask:0xf bank_mask:0xf bound_ctrl:1
	v_add_f32_dpp v169, v169, v169 row_half_mirror row_mask:0xf bank_mask:0xf bound_ctrl:1
	v_add_f32_dpp v170, v170, v170 row_half_mirror row_mask:0xf bank_mask:0xf bound_ctrl:1
	v_add_f32_dpp v168, v168, v168 quad_perm:[1,0,3,2] row_mask:0xf bank_mask:0xf bound_ctrl:1
	v_add_f32_dpp v166, v166, v166 quad_perm:[1,0,3,2] row_mask:0xf bank_mask:0xf bound_ctrl:1
	v_add_f32_dpp v169, v169, v169 quad_perm:[1,0,3,2] row_mask:0xf bank_mask:0xf bound_ctrl:1
	v_add_f32_dpp v170, v170, v170 quad_perm:[1,0,3,2] row_mask:0xf bank_mask:0xf bound_ctrl:1
	v_add_f32_dpp v168, v168, v168 quad_perm:[2,3,0,1] row_mask:0xf bank_mask:0xf bound_ctrl:1
	v_add_f32_dpp v166, v166, v166 quad_perm:[2,3,0,1] row_mask:0xf bank_mask:0xf bound_ctrl:1
	v_add_f32_dpp v169, v169, v169 quad_perm:[2,3,0,1] row_mask:0xf bank_mask:0xf bound_ctrl:1
	v_add_f32_dpp v170, v170, v170 quad_perm:[2,3,0,1] row_mask:0xf bank_mask:0xf bound_ctrl:1
	v_fma_f32 v164, v40, v37, v169
	v_fma_f32 v171, v40, v39, v170
	v_pk_fma_f32 v[148:149], v[20:21], v[166:167], v[148:149] op_sel_hi:[1,0,1]
	v_fma_f32 v167, v166, v36, v164
	v_pk_fma_f32 v[150:151], v[22:23], v[166:167], v[150:151] op_sel_hi:[1,0,1]
	v_fma_f32 v171, v166, v38, v171
	v_cndmask_b32_e64 v162, v162, v168, s[52:53]
	v_pk_fma_f32 v[148:149], v[28:29], v[166:167], v[148:149] op_sel:[0,1,0] op_sel_hi:[1,1,1]
	v_pk_fma_f32 v[150:151], v[30:31], v[166:167], v[150:151] op_sel:[0,1,0] op_sel_hi:[1,1,1]
	v_cndmask_b32_e64 v162, v162, v171, s[54:55]
	v_pk_fma_f32 v[144:145], v[144:145], v[16:17], v[148:149]
	v_pk_fma_f32 v[146:147], v[146:147], v[18:19], v[150:151]
	s_waitcnt lgkmcnt(0)
	v_pk_mul_f32 v[96:97], v[144:145], v[12:13]
	v_pk_mul_f32 v[98:99], v[144:145], v[54:55]
	v_pk_mul_f32 v[100:101], v[144:145], v[58:59]
	v_pk_mul_f32 v[172:173], v[144:145], v[62:63]
	v_pk_fma_f32 v[96:97], v[146:147], v[14:15], v[96:97]
	v_pk_fma_f32 v[98:99], v[146:147], v[56:57], v[98:99]
	v_pk_fma_f32 v[100:101], v[146:147], v[60:61], v[100:101]
	v_pk_fma_f32 v[172:173], v[146:147], v[64:65], v[172:173]
	ds_read_b128 v[0:3], v174 offset:11392
	ds_read_b128 v[4:7], v174 offset:11648
	ds_read_b128 v[8:11], v174 offset:11904
	ds_read_b128 v[12:15], v174 offset:12160
	ds_read_b128 v[16:19], v174 offset:12416
	ds_read_b128 v[20:23], v174 offset:12672
	ds_read_b128 v[24:27], v174 offset:12928
	ds_read_b128 v[28:31], v174 offset:13184
	ds_read_b128 v[32:35], v174 offset:13440
	ds_read_b128 v[36:39], v175 offset:14208
	ds_read_b32 v40, v163 offset:13696
	ds_read_b32 v41, v163 offset:13952
	v_pk_mul_f32 v[148:149], v[78:79], v[94:95] op_sel_hi:[1,0]
	v_pk_mul_f32 v[150:151], v[80:81], v[94:95] op_sel_hi:[1,0]
	v_add_f32_e32 v168, v96, v97
	v_add_f32_e32 v166, v98, v99
	v_add_f32_e32 v169, v100, v101
	v_add_f32_e32 v170, v172, v173
	v_pk_fma_f32 v[148:149], v[86:87], v[94:95], v[148:149] op_sel:[0,1,0] op_sel_hi:[1,1,1]
	v_pk_fma_f32 v[150:151], v[88:89], v[94:95], v[150:151] op_sel:[0,1,0] op_sel_hi:[1,1,1]
	v_add_f32_dpp v168, v168, v168 row_mirror row_mask:0xf bank_mask:0xf bound_ctrl:1
	v_add_f32_dpp v166, v166, v166 row_mirror row_mask:0xf bank_mask:0xf bound_ctrl:1
	v_add_f32_dpp v169, v169, v169 row_mirror row_mask:0xf bank_mask:0xf bound_ctrl:1
	v_add_f32_dpp v170, v170, v170 row_mirror row_mask:0xf bank_mask:0xf bound_ctrl:1
	v_add_f32_dpp v168, v168, v168 row_half_mirror row_mask:0xf bank_mask:0xf bound_ctrl:1
	v_add_f32_dpp v166, v166, v166 row_half_mirror row_mask:0xf bank_mask:0xf bound_ctrl:1
	v_add_f32_dpp v169, v169, v169 row_half_mirror row_mask:0xf bank_mask:0xf bound_ctrl:1
	v_add_f32_dpp v170, v170, v170 row_half_mirror row_mask:0xf bank_mask:0xf bound_ctrl:1
	v_add_f32_dpp v168, v168, v168 quad_perm:[1,0,3,2] row_mask:0xf bank_mask:0xf bound_ctrl:1
	v_add_f32_dpp v166, v166, v166 quad_perm:[1,0,3,2] row_mask:0xf bank_mask:0xf bound_ctrl:1
	v_add_f32_dpp v169, v169, v169 quad_perm:[1,0,3,2] row_mask:0xf bank_mask:0xf bound_ctrl:1
	v_add_f32_dpp v170, v170, v170 quad_perm:[1,0,3,2] row_mask:0xf bank_mask:0xf bound_ctrl:1
	v_add_f32_dpp v168, v168, v168 quad_perm:[2,3,0,1] row_mask:0xf bank_mask:0xf bound_ctrl:1
	v_add_f32_dpp v166, v166, v166 quad_perm:[2,3,0,1] row_mask:0xf bank_mask:0xf bound_ctrl:1
	v_add_f32_dpp v169, v169, v169 quad_perm:[2,3,0,1] row_mask:0xf bank_mask:0xf bound_ctrl:1
	v_add_f32_dpp v170, v170, v170 quad_perm:[2,3,0,1] row_mask:0xf bank_mask:0xf bound_ctrl:1
	v_fma_f32 v164, v94, v91, v169
	v_fma_f32 v171, v94, v93, v170
	v_pk_fma_f32 v[148:149], v[74:75], v[166:167], v[148:149] op_sel_hi:[1,0,1]
	v_fma_f32 v167, v166, v90, v164
	v_pk_fma_f32 v[150:151], v[76:77], v[166:167], v[150:151] op_sel_hi:[1,0,1]
	v_fma_f32 v171, v166, v92, v171
	v_cndmask_b32_e64 v162, v162, v168, s[56:57]
	v_pk_fma_f32 v[148:149], v[82:83], v[166:167], v[148:149] op_sel:[0,1,0] op_sel_hi:[1,1,1]
	v_pk_fma_f32 v[150:151], v[84:85], v[166:167], v[150:151] op_sel:[0,1,0] op_sel_hi:[1,1,1]
	v_cndmask_b32_e64 v162, v162, v171, s[58:59]
	v_pk_fma_f32 v[144:145], v[144:145], v[70:71], v[148:149]
	v_pk_fma_f32 v[146:147], v[146:147], v[72:73], v[150:151]
	s_waitcnt lgkmcnt(0)
	v_pk_mul_f32 v[96:97], v[144:145], v[66:67]
	v_pk_mul_f32 v[98:99], v[144:145], v[0:1]
	v_pk_mul_f32 v[100:101], v[144:145], v[4:5]
	v_pk_mul_f32 v[172:173], v[144:145], v[8:9]
	v_pk_fma_f32 v[96:97], v[146:147], v[68:69], v[96:97]
	v_pk_fma_f32 v[98:99], v[146:147], v[2:3], v[98:99]
	v_pk_fma_f32 v[100:101], v[146:147], v[6:7], v[100:101]
	v_pk_fma_f32 v[172:173], v[146:147], v[10:11], v[172:173]
	ds_read_b128 v[54:57], v174 offset:14240
	ds_read_b128 v[58:61], v174 offset:14496
	ds_read_b128 v[62:65], v174 offset:14752
	ds_read_b128 v[66:69], v174 offset:15008
	ds_read_b128 v[70:73], v174 offset:15264
	ds_read_b128 v[74:77], v174 offset:15520
	ds_read_b128 v[78:81], v174 offset:15776
	ds_read_b128 v[82:85], v174 offset:16032
	ds_read_b128 v[86:89], v174 offset:16288
	ds_read_b128 v[90:93], v175 offset:17056
	ds_read_b32 v94, v163 offset:16544
	ds_read_b32 v95, v163 offset:16800
	v_pk_mul_f32 v[148:149], v[24:25], v[40:41] op_sel_hi:[1,0]
	v_pk_mul_f32 v[150:151], v[26:27], v[40:41] op_sel_hi:[1,0]
	v_add_f32_e32 v168, v96, v97
	v_add_f32_e32 v166, v98, v99
	v_add_f32_e32 v169, v100, v101
	v_add_f32_e32 v170, v172, v173
	v_pk_fma_f32 v[148:149], v[32:33], v[40:41], v[148:149] op_sel:[0,1,0] op_sel_hi:[1,1,1]
	v_pk_fma_f32 v[150:151], v[34:35], v[40:41], v[150:151] op_sel:[0,1,0] op_sel_hi:[1,1,1]
	v_add_f32_dpp v168, v168, v168 row_mirror row_mask:0xf bank_mask:0xf bound_ctrl:1
	v_add_f32_dpp v166, v166, v166 row_mirror row_mask:0xf bank_mask:0xf bound_ctrl:1
	v_add_f32_dpp v169, v169, v169 row_mirror row_mask:0xf bank_mask:0xf bound_ctrl:1
	v_add_f32_dpp v170, v170, v170 row_mirror row_mask:0xf bank_mask:0xf bound_ctrl:1
	v_add_f32_dpp v168, v168, v168 row_half_mirror row_mask:0xf bank_mask:0xf bound_ctrl:1
	v_add_f32_dpp v166, v166, v166 row_half_mirror row_mask:0xf bank_mask:0xf bound_ctrl:1
	v_add_f32_dpp v169, v169, v169 row_half_mirror row_mask:0xf bank_mask:0xf bound_ctrl:1
	v_add_f32_dpp v170, v170, v170 row_half_mirror row_mask:0xf bank_mask:0xf bound_ctrl:1
	v_add_f32_dpp v168, v168, v168 quad_perm:[1,0,3,2] row_mask:0xf bank_mask:0xf bound_ctrl:1
	v_add_f32_dpp v166, v166, v166 quad_perm:[1,0,3,2] row_mask:0xf bank_mask:0xf bound_ctrl:1
	v_add_f32_dpp v169, v169, v169 quad_perm:[1,0,3,2] row_mask:0xf bank_mask:0xf bound_ctrl:1
	v_add_f32_dpp v170, v170, v170 quad_perm:[1,0,3,2] row_mask:0xf bank_mask:0xf bound_ctrl:1
	v_add_f32_dpp v168, v168, v168 quad_perm:[2,3,0,1] row_mask:0xf bank_mask:0xf bound_ctrl:1
	v_add_f32_dpp v166, v166, v166 quad_perm:[2,3,0,1] row_mask:0xf bank_mask:0xf bound_ctrl:1
	v_add_f32_dpp v169, v169, v169 quad_perm:[2,3,0,1] row_mask:0xf bank_mask:0xf bound_ctrl:1
	v_add_f32_dpp v170, v170, v170 quad_perm:[2,3,0,1] row_mask:0xf bank_mask:0xf bound_ctrl:1
	v_fma_f32 v164, v40, v37, v169
	v_fma_f32 v171, v40, v39, v170
	v_pk_fma_f32 v[148:149], v[20:21], v[166:167], v[148:149] op_sel_hi:[1,0,1]
	v_fma_f32 v167, v166, v36, v164
	v_pk_fma_f32 v[150:151], v[22:23], v[166:167], v[150:151] op_sel_hi:[1,0,1]
	v_fma_f32 v171, v166, v38, v171
	v_cndmask_b32_e64 v162, v162, v168, s[60:61]
	v_pk_fma_f32 v[148:149], v[28:29], v[166:167], v[148:149] op_sel:[0,1,0] op_sel_hi:[1,1,1]
	v_pk_fma_f32 v[150:151], v[30:31], v[166:167], v[150:151] op_sel:[0,1,0] op_sel_hi:[1,1,1]
	v_cndmask_b32_e64 v162, v162, v171, s[62:63]
	v_pk_fma_f32 v[144:145], v[144:145], v[16:17], v[148:149]
	v_pk_fma_f32 v[146:147], v[146:147], v[18:19], v[150:151]
	s_waitcnt lgkmcnt(0)
	v_pk_mul_f32 v[96:97], v[144:145], v[12:13]
	v_pk_mul_f32 v[98:99], v[144:145], v[54:55]
	v_pk_mul_f32 v[100:101], v[144:145], v[58:59]
	v_pk_mul_f32 v[172:173], v[144:145], v[62:63]
	v_pk_fma_f32 v[96:97], v[146:147], v[14:15], v[96:97]
	v_pk_fma_f32 v[98:99], v[146:147], v[56:57], v[98:99]
	v_pk_fma_f32 v[100:101], v[146:147], v[60:61], v[100:101]
	v_pk_fma_f32 v[172:173], v[146:147], v[64:65], v[172:173]
	ds_read_b128 v[0:3], v174 offset:17088
	ds_read_b128 v[4:7], v174 offset:17344
	ds_read_b128 v[8:11], v174 offset:17600
	ds_read_b128 v[12:15], v174 offset:17856
	ds_read_b128 v[16:19], v174 offset:18112
	ds_read_b128 v[20:23], v174 offset:18368
	ds_read_b128 v[24:27], v174 offset:18624
	ds_read_b128 v[28:31], v174 offset:18880
	ds_read_b128 v[32:35], v174 offset:19136
	ds_read_b128 v[36:39], v175 offset:19904
	ds_read_b32 v40, v163 offset:19392
	ds_read_b32 v41, v163 offset:19648
	v_pk_mul_f32 v[148:149], v[78:79], v[94:95] op_sel_hi:[1,0]
	v_pk_mul_f32 v[150:151], v[80:81], v[94:95] op_sel_hi:[1,0]
	v_add_f32_e32 v168, v96, v97
	v_add_f32_e32 v166, v98, v99
	v_add_f32_e32 v169, v100, v101
	v_add_f32_e32 v170, v172, v173
	v_pk_fma_f32 v[148:149], v[86:87], v[94:95], v[148:149] op_sel:[0,1,0] op_sel_hi:[1,1,1]
	v_pk_fma_f32 v[150:151], v[88:89], v[94:95], v[150:151] op_sel:[0,1,0] op_sel_hi:[1,1,1]
	v_add_f32_dpp v168, v168, v168 row_mirror row_mask:0xf bank_mask:0xf bound_ctrl:1
	v_add_f32_dpp v166, v166, v166 row_mirror row_mask:0xf bank_mask:0xf bound_ctrl:1
	v_add_f32_dpp v169, v169, v169 row_mirror row_mask:0xf bank_mask:0xf bound_ctrl:1
	v_add_f32_dpp v170, v170, v170 row_mirror row_mask:0xf bank_mask:0xf bound_ctrl:1
	v_add_f32_dpp v168, v168, v168 row_half_mirror row_mask:0xf bank_mask:0xf bound_ctrl:1
	v_add_f32_dpp v166, v166, v166 row_half_mirror row_mask:0xf bank_mask:0xf bound_ctrl:1
	v_add_f32_dpp v169, v169, v169 row_half_mirror row_mask:0xf bank_mask:0xf bound_ctrl:1
	v_add_f32_dpp v170, v170, v170 row_half_mirror row_mask:0xf bank_mask:0xf bound_ctrl:1
	v_add_f32_dpp v168, v168, v168 quad_perm:[1,0,3,2] row_mask:0xf bank_mask:0xf bound_ctrl:1
	v_add_f32_dpp v166, v166, v166 quad_perm:[1,0,3,2] row_mask:0xf bank_mask:0xf bound_ctrl:1
	v_add_f32_dpp v169, v169, v169 quad_perm:[1,0,3,2] row_mask:0xf bank_mask:0xf bound_ctrl:1
	v_add_f32_dpp v170, v170, v170 quad_perm:[1,0,3,2] row_mask:0xf bank_mask:0xf bound_ctrl:1
	v_add_f32_dpp v168, v168, v168 quad_perm:[2,3,0,1] row_mask:0xf bank_mask:0xf bound_ctrl:1
	v_add_f32_dpp v166, v166, v166 quad_perm:[2,3,0,1] row_mask:0xf bank_mask:0xf bound_ctrl:1
	v_add_f32_dpp v169, v169, v169 quad_perm:[2,3,0,1] row_mask:0xf bank_mask:0xf bound_ctrl:1
	v_add_f32_dpp v170, v170, v170 quad_perm:[2,3,0,1] row_mask:0xf bank_mask:0xf bound_ctrl:1
	v_fma_f32 v164, v94, v91, v169
	v_fma_f32 v171, v94, v93, v170
	v_pk_fma_f32 v[148:149], v[74:75], v[166:167], v[148:149] op_sel_hi:[1,0,1]
	v_fma_f32 v167, v166, v90, v164
	v_pk_fma_f32 v[150:151], v[76:77], v[166:167], v[150:151] op_sel_hi:[1,0,1]
	v_fma_f32 v171, v166, v92, v171
	v_cndmask_b32_e64 v162, v162, v168, s[64:65]
	v_pk_fma_f32 v[148:149], v[82:83], v[166:167], v[148:149] op_sel:[0,1,0] op_sel_hi:[1,1,1]
	v_pk_fma_f32 v[150:151], v[84:85], v[166:167], v[150:151] op_sel:[0,1,0] op_sel_hi:[1,1,1]
	v_cndmask_b32_e64 v162, v162, v171, s[66:67]
	v_pk_fma_f32 v[144:145], v[144:145], v[70:71], v[148:149]
	v_pk_fma_f32 v[146:147], v[146:147], v[72:73], v[150:151]
	s_waitcnt lgkmcnt(0)
	v_pk_mul_f32 v[96:97], v[144:145], v[66:67]
	v_pk_mul_f32 v[98:99], v[144:145], v[0:1]
	v_pk_mul_f32 v[100:101], v[144:145], v[4:5]
	v_pk_mul_f32 v[172:173], v[144:145], v[8:9]
	v_pk_fma_f32 v[96:97], v[146:147], v[68:69], v[96:97]
	v_pk_fma_f32 v[98:99], v[146:147], v[2:3], v[98:99]
	v_pk_fma_f32 v[100:101], v[146:147], v[6:7], v[100:101]
	v_pk_fma_f32 v[172:173], v[146:147], v[10:11], v[172:173]
	ds_read_b128 v[54:57], v174 offset:19936
	ds_read_b128 v[58:61], v174 offset:20192
	ds_read_b128 v[62:65], v174 offset:20448
	ds_read_b128 v[66:69], v174 offset:20704
	ds_read_b128 v[70:73], v174 offset:20960
	ds_read_b128 v[74:77], v174 offset:21216
	ds_read_b128 v[78:81], v174 offset:21472
	ds_read_b128 v[82:85], v174 offset:21728
	ds_read_b128 v[86:89], v174 offset:21984
	ds_read_b128 v[90:93], v175 offset:22752
	ds_read_b32 v94, v163 offset:22240
	ds_read_b32 v95, v163 offset:22496
	v_pk_mul_f32 v[148:149], v[24:25], v[40:41] op_sel_hi:[1,0]
	v_pk_mul_f32 v[150:151], v[26:27], v[40:41] op_sel_hi:[1,0]
	v_add_f32_e32 v168, v96, v97
	v_add_f32_e32 v166, v98, v99
	v_add_f32_e32 v169, v100, v101
	v_add_f32_e32 v170, v172, v173
	v_pk_fma_f32 v[148:149], v[32:33], v[40:41], v[148:149] op_sel:[0,1,0] op_sel_hi:[1,1,1]
	v_pk_fma_f32 v[150:151], v[34:35], v[40:41], v[150:151] op_sel:[0,1,0] op_sel_hi:[1,1,1]
	v_add_f32_dpp v168, v168, v168 row_mirror row_mask:0xf bank_mask:0xf bound_ctrl:1
	v_add_f32_dpp v166, v166, v166 row_mirror row_mask:0xf bank_mask:0xf bound_ctrl:1
	v_add_f32_dpp v169, v169, v169 row_mirror row_mask:0xf bank_mask:0xf bound_ctrl:1
	v_add_f32_dpp v170, v170, v170 row_mirror row_mask:0xf bank_mask:0xf bound_ctrl:1
	v_add_f32_dpp v168, v168, v168 row_half_mirror row_mask:0xf bank_mask:0xf bound_ctrl:1
	v_add_f32_dpp v166, v166, v166 row_half_mirror row_mask:0xf bank_mask:0xf bound_ctrl:1
	v_add_f32_dpp v169, v169, v169 row_half_mirror row_mask:0xf bank_mask:0xf bound_ctrl:1
	v_add_f32_dpp v170, v170, v170 row_half_mirror row_mask:0xf bank_mask:0xf bound_ctrl:1
	v_add_f32_dpp v168, v168, v168 quad_perm:[1,0,3,2] row_mask:0xf bank_mask:0xf bound_ctrl:1
	v_add_f32_dpp v166, v166, v166 quad_perm:[1,0,3,2] row_mask:0xf bank_mask:0xf bound_ctrl:1
	v_add_f32_dpp v169, v169, v169 quad_perm:[1,0,3,2] row_mask:0xf bank_mask:0xf bound_ctrl:1
	v_add_f32_dpp v170, v170, v170 quad_perm:[1,0,3,2] row_mask:0xf bank_mask:0xf bound_ctrl:1
	v_add_f32_dpp v168, v168, v168 quad_perm:[2,3,0,1] row_mask:0xf bank_mask:0xf bound_ctrl:1
	v_add_f32_dpp v166, v166, v166 quad_perm:[2,3,0,1] row_mask:0xf bank_mask:0xf bound_ctrl:1
	v_add_f32_dpp v169, v169, v169 quad_perm:[2,3,0,1] row_mask:0xf bank_mask:0xf bound_ctrl:1
	v_add_f32_dpp v170, v170, v170 quad_perm:[2,3,0,1] row_mask:0xf bank_mask:0xf bound_ctrl:1
	v_fma_f32 v164, v40, v37, v169
	v_fma_f32 v171, v40, v39, v170
	v_pk_fma_f32 v[148:149], v[20:21], v[166:167], v[148:149] op_sel_hi:[1,0,1]
	v_fma_f32 v167, v166, v36, v164
	v_pk_fma_f32 v[150:151], v[22:23], v[166:167], v[150:151] op_sel_hi:[1,0,1]
	v_fma_f32 v171, v166, v38, v171
	v_cndmask_b32_e64 v162, v162, v168, s[68:69]
	v_pk_fma_f32 v[148:149], v[28:29], v[166:167], v[148:149] op_sel:[0,1,0] op_sel_hi:[1,1,1]
	v_pk_fma_f32 v[150:151], v[30:31], v[166:167], v[150:151] op_sel:[0,1,0] op_sel_hi:[1,1,1]
	v_cndmask_b32_e64 v162, v162, v171, s[70:71]
	v_pk_fma_f32 v[144:145], v[144:145], v[16:17], v[148:149]
	v_pk_fma_f32 v[146:147], v[146:147], v[18:19], v[150:151]
	s_waitcnt lgkmcnt(0)
	v_pk_mul_f32 v[96:97], v[144:145], v[12:13]
	v_pk_mul_f32 v[98:99], v[144:145], v[54:55]
	v_pk_mul_f32 v[100:101], v[144:145], v[58:59]
	v_pk_mul_f32 v[172:173], v[144:145], v[62:63]
	v_pk_fma_f32 v[96:97], v[146:147], v[14:15], v[96:97]
	v_pk_fma_f32 v[98:99], v[146:147], v[56:57], v[98:99]
	v_pk_fma_f32 v[100:101], v[146:147], v[60:61], v[100:101]
	v_pk_fma_f32 v[172:173], v[146:147], v[64:65], v[172:173]
	ds_read_b128 v[0:3], v174 offset:22784
	ds_read_b128 v[4:7], v174 offset:23040
	ds_read_b128 v[8:11], v174 offset:23296
	ds_read_b128 v[12:15], v174 offset:23552
	ds_read_b128 v[16:19], v174 offset:23808
	ds_read_b128 v[20:23], v174 offset:24064
	ds_read_b128 v[24:27], v174 offset:24320
	ds_read_b128 v[28:31], v174 offset:24576
	ds_read_b128 v[32:35], v174 offset:24832
	ds_read_b128 v[36:39], v175 offset:25600
	ds_read_b32 v40, v163 offset:25088
	ds_read_b32 v41, v163 offset:25344
	v_pk_mul_f32 v[148:149], v[78:79], v[94:95] op_sel_hi:[1,0]
	v_pk_mul_f32 v[150:151], v[80:81], v[94:95] op_sel_hi:[1,0]
	v_add_f32_e32 v168, v96, v97
	v_add_f32_e32 v166, v98, v99
	v_add_f32_e32 v169, v100, v101
	v_add_f32_e32 v170, v172, v173
	v_pk_fma_f32 v[148:149], v[86:87], v[94:95], v[148:149] op_sel:[0,1,0] op_sel_hi:[1,1,1]
	v_pk_fma_f32 v[150:151], v[88:89], v[94:95], v[150:151] op_sel:[0,1,0] op_sel_hi:[1,1,1]
	v_add_f32_dpp v168, v168, v168 row_mirror row_mask:0xf bank_mask:0xf bound_ctrl:1
	v_add_f32_dpp v166, v166, v166 row_mirror row_mask:0xf bank_mask:0xf bound_ctrl:1
	v_add_f32_dpp v169, v169, v169 row_mirror row_mask:0xf bank_mask:0xf bound_ctrl:1
	v_add_f32_dpp v170, v170, v170 row_mirror row_mask:0xf bank_mask:0xf bound_ctrl:1
	v_add_f32_dpp v168, v168, v168 row_half_mirror row_mask:0xf bank_mask:0xf bound_ctrl:1
	v_add_f32_dpp v166, v166, v166 row_half_mirror row_mask:0xf bank_mask:0xf bound_ctrl:1
	v_add_f32_dpp v169, v169, v169 row_half_mirror row_mask:0xf bank_mask:0xf bound_ctrl:1
	v_add_f32_dpp v170, v170, v170 row_half_mirror row_mask:0xf bank_mask:0xf bound_ctrl:1
	v_add_f32_dpp v168, v168, v168 quad_perm:[1,0,3,2] row_mask:0xf bank_mask:0xf bound_ctrl:1
	v_add_f32_dpp v166, v166, v166 quad_perm:[1,0,3,2] row_mask:0xf bank_mask:0xf bound_ctrl:1
	v_add_f32_dpp v169, v169, v169 quad_perm:[1,0,3,2] row_mask:0xf bank_mask:0xf bound_ctrl:1
	v_add_f32_dpp v170, v170, v170 quad_perm:[1,0,3,2] row_mask:0xf bank_mask:0xf bound_ctrl:1
	v_add_f32_dpp v168, v168, v168 quad_perm:[2,3,0,1] row_mask:0xf bank_mask:0xf bound_ctrl:1
	v_add_f32_dpp v166, v166, v166 quad_perm:[2,3,0,1] row_mask:0xf bank_mask:0xf bound_ctrl:1
	v_add_f32_dpp v169, v169, v169 quad_perm:[2,3,0,1] row_mask:0xf bank_mask:0xf bound_ctrl:1
	v_add_f32_dpp v170, v170, v170 quad_perm:[2,3,0,1] row_mask:0xf bank_mask:0xf bound_ctrl:1
	v_fma_f32 v164, v94, v91, v169
	v_fma_f32 v171, v94, v93, v170
	v_pk_fma_f32 v[148:149], v[74:75], v[166:167], v[148:149] op_sel_hi:[1,0,1]
	v_fma_f32 v167, v166, v90, v164
	v_pk_fma_f32 v[150:151], v[76:77], v[166:167], v[150:151] op_sel_hi:[1,0,1]
	v_fma_f32 v171, v166, v92, v171
	v_cndmask_b32_e64 v162, v162, v168, s[44:45]
	v_pk_fma_f32 v[148:149], v[82:83], v[166:167], v[148:149] op_sel:[0,1,0] op_sel_hi:[1,1,1]
	v_pk_fma_f32 v[150:151], v[84:85], v[166:167], v[150:151] op_sel:[0,1,0] op_sel_hi:[1,1,1]
	v_cndmask_b32_e64 v162, v162, v171, s[42:43]
	v_pk_fma_f32 v[144:145], v[144:145], v[70:71], v[148:149]
	v_pk_fma_f32 v[146:147], v[146:147], v[72:73], v[150:151]
	s_waitcnt lgkmcnt(0)
	v_pk_mul_f32 v[96:97], v[144:145], v[66:67]
	v_pk_mul_f32 v[98:99], v[144:145], v[0:1]
	v_pk_mul_f32 v[100:101], v[144:145], v[4:5]
	v_pk_mul_f32 v[172:173], v[144:145], v[8:9]
	v_pk_fma_f32 v[96:97], v[146:147], v[68:69], v[96:97]
	v_pk_fma_f32 v[98:99], v[146:147], v[2:3], v[98:99]
	v_pk_fma_f32 v[100:101], v[146:147], v[6:7], v[100:101]
	v_pk_fma_f32 v[172:173], v[146:147], v[10:11], v[172:173]
	ds_read_b128 v[54:57], v174 offset:25632
	ds_read_b128 v[58:61], v174 offset:25888
	ds_read_b128 v[62:65], v174 offset:26144
	ds_read_b128 v[66:69], v174 offset:26400
	ds_read_b128 v[70:73], v174 offset:26656
	ds_read_b128 v[74:77], v174 offset:26912
	ds_read_b128 v[78:81], v174 offset:27168
	ds_read_b128 v[82:85], v174 offset:27424
	ds_read_b128 v[86:89], v174 offset:27680
	ds_read_b128 v[90:93], v175 offset:28448
	ds_read_b32 v94, v163 offset:27936
	ds_read_b32 v95, v163 offset:28192
	v_pk_mul_f32 v[148:149], v[24:25], v[40:41] op_sel_hi:[1,0]
	v_pk_mul_f32 v[150:151], v[26:27], v[40:41] op_sel_hi:[1,0]
	v_add_f32_e32 v168, v96, v97
	v_add_f32_e32 v166, v98, v99
	v_add_f32_e32 v169, v100, v101
	v_add_f32_e32 v170, v172, v173
	v_pk_fma_f32 v[148:149], v[32:33], v[40:41], v[148:149] op_sel:[0,1,0] op_sel_hi:[1,1,1]
	v_pk_fma_f32 v[150:151], v[34:35], v[40:41], v[150:151] op_sel:[0,1,0] op_sel_hi:[1,1,1]
	v_add_f32_dpp v168, v168, v168 row_mirror row_mask:0xf bank_mask:0xf bound_ctrl:1
	v_add_f32_dpp v166, v166, v166 row_mirror row_mask:0xf bank_mask:0xf bound_ctrl:1
	v_add_f32_dpp v169, v169, v169 row_mirror row_mask:0xf bank_mask:0xf bound_ctrl:1
	v_add_f32_dpp v170, v170, v170 row_mirror row_mask:0xf bank_mask:0xf bound_ctrl:1
	v_add_f32_dpp v168, v168, v168 row_half_mirror row_mask:0xf bank_mask:0xf bound_ctrl:1
	v_add_f32_dpp v166, v166, v166 row_half_mirror row_mask:0xf bank_mask:0xf bound_ctrl:1
	v_add_f32_dpp v169, v169, v169 row_half_mirror row_mask:0xf bank_mask:0xf bound_ctrl:1
	v_add_f32_dpp v170, v170, v170 row_half_mirror row_mask:0xf bank_mask:0xf bound_ctrl:1
	v_add_f32_dpp v168, v168, v168 quad_perm:[1,0,3,2] row_mask:0xf bank_mask:0xf bound_ctrl:1
	v_add_f32_dpp v166, v166, v166 quad_perm:[1,0,3,2] row_mask:0xf bank_mask:0xf bound_ctrl:1
	v_add_f32_dpp v169, v169, v169 quad_perm:[1,0,3,2] row_mask:0xf bank_mask:0xf bound_ctrl:1
	v_add_f32_dpp v170, v170, v170 quad_perm:[1,0,3,2] row_mask:0xf bank_mask:0xf bound_ctrl:1
	v_add_f32_dpp v168, v168, v168 quad_perm:[2,3,0,1] row_mask:0xf bank_mask:0xf bound_ctrl:1
	v_add_f32_dpp v166, v166, v166 quad_perm:[2,3,0,1] row_mask:0xf bank_mask:0xf bound_ctrl:1
	v_add_f32_dpp v169, v169, v169 quad_perm:[2,3,0,1] row_mask:0xf bank_mask:0xf bound_ctrl:1
	v_add_f32_dpp v170, v170, v170 quad_perm:[2,3,0,1] row_mask:0xf bank_mask:0xf bound_ctrl:1
	v_fma_f32 v164, v40, v37, v169
	v_fma_f32 v171, v40, v39, v170
	v_pk_fma_f32 v[148:149], v[20:21], v[166:167], v[148:149] op_sel_hi:[1,0,1]
	v_fma_f32 v167, v166, v36, v164
	v_pk_fma_f32 v[150:151], v[22:23], v[166:167], v[150:151] op_sel_hi:[1,0,1]
	v_fma_f32 v171, v166, v38, v171
	v_cndmask_b32_e64 v162, v162, v168, s[46:47]
	s_lshl_b32 s6, s9, 1
	s_add_i32 s6, s6, 1
	s_add_i32 s6, s6, -1
	s_and_b32 s6, s6, 7
	s_lshl_b32 s6, s6, 10
	v_add_u32_e32 v161, s6, v156
	ds_write_b32 v161, v162
	v_pk_fma_f32 v[148:149], v[28:29], v[166:167], v[148:149] op_sel:[0,1,0] op_sel_hi:[1,1,1]
	v_pk_fma_f32 v[150:151], v[30:31], v[166:167], v[150:151] op_sel:[0,1,0] op_sel_hi:[1,1,1]
	v_cndmask_b32_e64 v162, v162, v171, s[38:39]
	v_pk_fma_f32 v[144:145], v[144:145], v[16:17], v[148:149]
	v_pk_fma_f32 v[146:147], v[146:147], v[18:19], v[150:151]
	s_waitcnt lgkmcnt(0)
	v_pk_mul_f32 v[96:97], v[144:145], v[12:13]
	v_pk_mul_f32 v[98:99], v[144:145], v[54:55]
	v_pk_mul_f32 v[100:101], v[144:145], v[58:59]
	v_pk_mul_f32 v[172:173], v[144:145], v[62:63]
	v_pk_fma_f32 v[96:97], v[146:147], v[14:15], v[96:97]
	v_pk_fma_f32 v[98:99], v[146:147], v[56:57], v[98:99]
	v_pk_fma_f32 v[100:101], v[146:147], v[60:61], v[100:101]
	v_pk_fma_f32 v[172:173], v[146:147], v[64:65], v[172:173]
	ds_read_b128 v[0:3], v174 offset:28480
	ds_read_b128 v[4:7], v174 offset:28736
	ds_read_b128 v[8:11], v174 offset:28992
	ds_read_b128 v[12:15], v174 offset:29248
	ds_read_b128 v[16:19], v174 offset:29504
	ds_read_b128 v[20:23], v174 offset:29760
	ds_read_b128 v[24:27], v174 offset:30016
	ds_read_b128 v[28:31], v174 offset:30272
	ds_read_b128 v[32:35], v174 offset:30528
	ds_read_b128 v[36:39], v175 offset:31296
	ds_read_b32 v40, v163 offset:30784
	ds_read_b32 v41, v163 offset:31040
	v_pk_mul_f32 v[148:149], v[78:79], v[94:95] op_sel_hi:[1,0]
	v_pk_mul_f32 v[150:151], v[80:81], v[94:95] op_sel_hi:[1,0]
	v_add_f32_e32 v168, v96, v97
	v_add_f32_e32 v166, v98, v99
	v_add_f32_e32 v169, v100, v101
	v_add_f32_e32 v170, v172, v173
	v_pk_fma_f32 v[148:149], v[86:87], v[94:95], v[148:149] op_sel:[0,1,0] op_sel_hi:[1,1,1]
	v_pk_fma_f32 v[150:151], v[88:89], v[94:95], v[150:151] op_sel:[0,1,0] op_sel_hi:[1,1,1]
	v_add_f32_dpp v168, v168, v168 row_mirror row_mask:0xf bank_mask:0xf bound_ctrl:1
	v_add_f32_dpp v166, v166, v166 row_mirror row_mask:0xf bank_mask:0xf bound_ctrl:1
	v_add_f32_dpp v169, v169, v169 row_mirror row_mask:0xf bank_mask:0xf bound_ctrl:1
	v_add_f32_dpp v170, v170, v170 row_mirror row_mask:0xf bank_mask:0xf bound_ctrl:1
	v_add_f32_dpp v168, v168, v168 row_half_mirror row_mask:0xf bank_mask:0xf bound_ctrl:1
	v_add_f32_dpp v166, v166, v166 row_half_mirror row_mask:0xf bank_mask:0xf bound_ctrl:1
	v_add_f32_dpp v169, v169, v169 row_half_mirror row_mask:0xf bank_mask:0xf bound_ctrl:1
	v_add_f32_dpp v170, v170, v170 row_half_mirror row_mask:0xf bank_mask:0xf bound_ctrl:1
	v_add_f32_dpp v168, v168, v168 quad_perm:[1,0,3,2] row_mask:0xf bank_mask:0xf bound_ctrl:1
	v_add_f32_dpp v166, v166, v166 quad_perm:[1,0,3,2] row_mask:0xf bank_mask:0xf bound_ctrl:1
	v_add_f32_dpp v169, v169, v169 quad_perm:[1,0,3,2] row_mask:0xf bank_mask:0xf bound_ctrl:1
	v_add_f32_dpp v170, v170, v170 quad_perm:[1,0,3,2] row_mask:0xf bank_mask:0xf bound_ctrl:1
	v_add_f32_dpp v168, v168, v168 quad_perm:[2,3,0,1] row_mask:0xf bank_mask:0xf bound_ctrl:1
	v_add_f32_dpp v166, v166, v166 quad_perm:[2,3,0,1] row_mask:0xf bank_mask:0xf bound_ctrl:1
	v_add_f32_dpp v169, v169, v169 quad_perm:[2,3,0,1] row_mask:0xf bank_mask:0xf bound_ctrl:1
	v_add_f32_dpp v170, v170, v170 quad_perm:[2,3,0,1] row_mask:0xf bank_mask:0xf bound_ctrl:1
	v_fma_f32 v164, v94, v91, v169
	v_fma_f32 v171, v94, v93, v170
	v_pk_fma_f32 v[148:149], v[74:75], v[166:167], v[148:149] op_sel_hi:[1,0,1]
	v_fma_f32 v167, v166, v90, v164
	v_pk_fma_f32 v[150:151], v[76:77], v[166:167], v[150:151] op_sel_hi:[1,0,1]
	v_fma_f32 v171, v166, v92, v171
	v_cndmask_b32_e64 v162, v162, v168, s[48:49]
	v_pk_fma_f32 v[148:149], v[82:83], v[166:167], v[148:149] op_sel:[0,1,0] op_sel_hi:[1,1,1]
	v_pk_fma_f32 v[150:151], v[84:85], v[166:167], v[150:151] op_sel:[0,1,0] op_sel_hi:[1,1,1]
	v_cndmask_b32_e64 v162, v162, v171, s[50:51]
	v_pk_fma_f32 v[144:145], v[144:145], v[70:71], v[148:149]
	v_pk_fma_f32 v[146:147], v[146:147], v[72:73], v[150:151]
	s_waitcnt lgkmcnt(0)
	v_pk_mul_f32 v[96:97], v[144:145], v[66:67]
	v_pk_mul_f32 v[98:99], v[144:145], v[0:1]
	v_pk_mul_f32 v[100:101], v[144:145], v[4:5]
	v_pk_mul_f32 v[172:173], v[144:145], v[8:9]
	v_pk_fma_f32 v[96:97], v[146:147], v[68:69], v[96:97]
	v_pk_fma_f32 v[98:99], v[146:147], v[2:3], v[98:99]
	v_pk_fma_f32 v[100:101], v[146:147], v[6:7], v[100:101]
	v_pk_fma_f32 v[172:173], v[146:147], v[10:11], v[172:173]
	ds_read_b128 v[54:57], v174 offset:31328
	ds_read_b128 v[58:61], v174 offset:31584
	ds_read_b128 v[62:65], v174 offset:31840
	ds_read_b128 v[66:69], v174 offset:32096
	ds_read_b128 v[70:73], v174 offset:32352
	ds_read_b128 v[74:77], v174 offset:32608
	ds_read_b128 v[78:81], v174 offset:32864
	ds_read_b128 v[82:85], v174 offset:33120
	ds_read_b128 v[86:89], v174 offset:33376
	ds_read_b128 v[90:93], v175 offset:34144
	ds_read_b32 v94, v163 offset:33632
	ds_read_b32 v95, v163 offset:33888
	v_pk_mul_f32 v[148:149], v[24:25], v[40:41] op_sel_hi:[1,0]
	v_pk_mul_f32 v[150:151], v[26:27], v[40:41] op_sel_hi:[1,0]
	v_add_f32_e32 v168, v96, v97
	v_add_f32_e32 v166, v98, v99
	v_add_f32_e32 v169, v100, v101
	v_add_f32_e32 v170, v172, v173
	v_pk_fma_f32 v[148:149], v[32:33], v[40:41], v[148:149] op_sel:[0,1,0] op_sel_hi:[1,1,1]
	v_pk_fma_f32 v[150:151], v[34:35], v[40:41], v[150:151] op_sel:[0,1,0] op_sel_hi:[1,1,1]
	v_add_f32_dpp v168, v168, v168 row_mirror row_mask:0xf bank_mask:0xf bound_ctrl:1
	v_add_f32_dpp v166, v166, v166 row_mirror row_mask:0xf bank_mask:0xf bound_ctrl:1
	v_add_f32_dpp v169, v169, v169 row_mirror row_mask:0xf bank_mask:0xf bound_ctrl:1
	v_add_f32_dpp v170, v170, v170 row_mirror row_mask:0xf bank_mask:0xf bound_ctrl:1
	v_add_f32_dpp v168, v168, v168 row_half_mirror row_mask:0xf bank_mask:0xf bound_ctrl:1
	v_add_f32_dpp v166, v166, v166 row_half_mirror row_mask:0xf bank_mask:0xf bound_ctrl:1
	v_add_f32_dpp v169, v169, v169 row_half_mirror row_mask:0xf bank_mask:0xf bound_ctrl:1
	v_add_f32_dpp v170, v170, v170 row_half_mirror row_mask:0xf bank_mask:0xf bound_ctrl:1
	v_add_f32_dpp v168, v168, v168 quad_perm:[1,0,3,2] row_mask:0xf bank_mask:0xf bound_ctrl:1
	v_add_f32_dpp v166, v166, v166 quad_perm:[1,0,3,2] row_mask:0xf bank_mask:0xf bound_ctrl:1
	v_add_f32_dpp v169, v169, v169 quad_perm:[1,0,3,2] row_mask:0xf bank_mask:0xf bound_ctrl:1
	v_add_f32_dpp v170, v170, v170 quad_perm:[1,0,3,2] row_mask:0xf bank_mask:0xf bound_ctrl:1
	v_add_f32_dpp v168, v168, v168 quad_perm:[2,3,0,1] row_mask:0xf bank_mask:0xf bound_ctrl:1
	v_add_f32_dpp v166, v166, v166 quad_perm:[2,3,0,1] row_mask:0xf bank_mask:0xf bound_ctrl:1
	v_add_f32_dpp v169, v169, v169 quad_perm:[2,3,0,1] row_mask:0xf bank_mask:0xf bound_ctrl:1
	v_add_f32_dpp v170, v170, v170 quad_perm:[2,3,0,1] row_mask:0xf bank_mask:0xf bound_ctrl:1
	v_fma_f32 v164, v40, v37, v169
	v_fma_f32 v171, v40, v39, v170
	v_pk_fma_f32 v[148:149], v[20:21], v[166:167], v[148:149] op_sel_hi:[1,0,1]
	v_fma_f32 v167, v166, v36, v164
	v_pk_fma_f32 v[150:151], v[22:23], v[166:167], v[150:151] op_sel_hi:[1,0,1]
	v_fma_f32 v171, v166, v38, v171
	v_cndmask_b32_e64 v162, v162, v168, s[52:53]
	v_pk_fma_f32 v[148:149], v[28:29], v[166:167], v[148:149] op_sel:[0,1,0] op_sel_hi:[1,1,1]
	v_pk_fma_f32 v[150:151], v[30:31], v[166:167], v[150:151] op_sel:[0,1,0] op_sel_hi:[1,1,1]
	v_cndmask_b32_e64 v162, v162, v171, s[54:55]
	v_pk_fma_f32 v[144:145], v[144:145], v[16:17], v[148:149]
	v_pk_fma_f32 v[146:147], v[146:147], v[18:19], v[150:151]
	s_waitcnt lgkmcnt(0)
	v_pk_mul_f32 v[96:97], v[144:145], v[12:13]
	v_pk_mul_f32 v[98:99], v[144:145], v[54:55]
	v_pk_mul_f32 v[100:101], v[144:145], v[58:59]
	v_pk_mul_f32 v[172:173], v[144:145], v[62:63]
	v_pk_fma_f32 v[96:97], v[146:147], v[14:15], v[96:97]
	v_pk_fma_f32 v[98:99], v[146:147], v[56:57], v[98:99]
	v_pk_fma_f32 v[100:101], v[146:147], v[60:61], v[100:101]
	v_pk_fma_f32 v[172:173], v[146:147], v[64:65], v[172:173]
	ds_read_b128 v[0:3], v174 offset:34176
	ds_read_b128 v[4:7], v174 offset:34432
	ds_read_b128 v[8:11], v174 offset:34688
	ds_read_b128 v[12:15], v174 offset:34944
	ds_read_b128 v[16:19], v174 offset:35200
	ds_read_b128 v[20:23], v174 offset:35456
	ds_read_b128 v[24:27], v174 offset:35712
	ds_read_b128 v[28:31], v174 offset:35968
	ds_read_b128 v[32:35], v174 offset:36224
	ds_read_b128 v[36:39], v175 offset:36992
	ds_read_b32 v40, v163 offset:36480
	ds_read_b32 v41, v163 offset:36736
	v_pk_mul_f32 v[148:149], v[78:79], v[94:95] op_sel_hi:[1,0]
	v_pk_mul_f32 v[150:151], v[80:81], v[94:95] op_sel_hi:[1,0]
	v_add_f32_e32 v168, v96, v97
	v_add_f32_e32 v166, v98, v99
	v_add_f32_e32 v169, v100, v101
	v_add_f32_e32 v170, v172, v173
	v_pk_fma_f32 v[148:149], v[86:87], v[94:95], v[148:149] op_sel:[0,1,0] op_sel_hi:[1,1,1]
	v_pk_fma_f32 v[150:151], v[88:89], v[94:95], v[150:151] op_sel:[0,1,0] op_sel_hi:[1,1,1]
	v_add_f32_dpp v168, v168, v168 row_mirror row_mask:0xf bank_mask:0xf bound_ctrl:1
	v_add_f32_dpp v166, v166, v166 row_mirror row_mask:0xf bank_mask:0xf bound_ctrl:1
	v_add_f32_dpp v169, v169, v169 row_mirror row_mask:0xf bank_mask:0xf bound_ctrl:1
	v_add_f32_dpp v170, v170, v170 row_mirror row_mask:0xf bank_mask:0xf bound_ctrl:1
	v_add_f32_dpp v168, v168, v168 row_half_mirror row_mask:0xf bank_mask:0xf bound_ctrl:1
	v_add_f32_dpp v166, v166, v166 row_half_mirror row_mask:0xf bank_mask:0xf bound_ctrl:1
	v_add_f32_dpp v169, v169, v169 row_half_mirror row_mask:0xf bank_mask:0xf bound_ctrl:1
	v_add_f32_dpp v170, v170, v170 row_half_mirror row_mask:0xf bank_mask:0xf bound_ctrl:1
	v_add_f32_dpp v168, v168, v168 quad_perm:[1,0,3,2] row_mask:0xf bank_mask:0xf bound_ctrl:1
	v_add_f32_dpp v166, v166, v166 quad_perm:[1,0,3,2] row_mask:0xf bank_mask:0xf bound_ctrl:1
	v_add_f32_dpp v169, v169, v169 quad_perm:[1,0,3,2] row_mask:0xf bank_mask:0xf bound_ctrl:1
	v_add_f32_dpp v170, v170, v170 quad_perm:[1,0,3,2] row_mask:0xf bank_mask:0xf bound_ctrl:1
	v_add_f32_dpp v168, v168, v168 quad_perm:[2,3,0,1] row_mask:0xf bank_mask:0xf bound_ctrl:1
	v_add_f32_dpp v166, v166, v166 quad_perm:[2,3,0,1] row_mask:0xf bank_mask:0xf bound_ctrl:1
	v_add_f32_dpp v169, v169, v169 quad_perm:[2,3,0,1] row_mask:0xf bank_mask:0xf bound_ctrl:1
	v_add_f32_dpp v170, v170, v170 quad_perm:[2,3,0,1] row_mask:0xf bank_mask:0xf bound_ctrl:1
	v_fma_f32 v164, v94, v91, v169
	v_fma_f32 v171, v94, v93, v170
	v_pk_fma_f32 v[148:149], v[74:75], v[166:167], v[148:149] op_sel_hi:[1,0,1]
	v_fma_f32 v167, v166, v90, v164
	v_pk_fma_f32 v[150:151], v[76:77], v[166:167], v[150:151] op_sel_hi:[1,0,1]
	v_fma_f32 v171, v166, v92, v171
	v_cndmask_b32_e64 v162, v162, v168, s[56:57]
	v_pk_fma_f32 v[148:149], v[82:83], v[166:167], v[148:149] op_sel:[0,1,0] op_sel_hi:[1,1,1]
	v_pk_fma_f32 v[150:151], v[84:85], v[166:167], v[150:151] op_sel:[0,1,0] op_sel_hi:[1,1,1]
	v_cndmask_b32_e64 v162, v162, v171, s[58:59]
	v_pk_fma_f32 v[144:145], v[144:145], v[70:71], v[148:149]
	v_pk_fma_f32 v[146:147], v[146:147], v[72:73], v[150:151]
	s_waitcnt lgkmcnt(0)
	v_pk_mul_f32 v[96:97], v[144:145], v[66:67]
	v_pk_mul_f32 v[98:99], v[144:145], v[0:1]
	v_pk_mul_f32 v[100:101], v[144:145], v[4:5]
	v_pk_mul_f32 v[172:173], v[144:145], v[8:9]
	v_pk_fma_f32 v[96:97], v[146:147], v[68:69], v[96:97]
	v_pk_fma_f32 v[98:99], v[146:147], v[2:3], v[98:99]
	v_pk_fma_f32 v[100:101], v[146:147], v[6:7], v[100:101]
	v_pk_fma_f32 v[172:173], v[146:147], v[10:11], v[172:173]
	ds_read_b128 v[54:57], v174 offset:37024
	ds_read_b128 v[58:61], v174 offset:37280
	ds_read_b128 v[62:65], v174 offset:37536
	ds_read_b128 v[66:69], v174 offset:37792
	ds_read_b128 v[70:73], v174 offset:38048
	ds_read_b128 v[74:77], v174 offset:38304
	ds_read_b128 v[78:81], v174 offset:38560
	ds_read_b128 v[82:85], v174 offset:38816
	ds_read_b128 v[86:89], v174 offset:39072
	ds_read_b128 v[90:93], v175 offset:39840
	ds_read_b32 v94, v163 offset:39328
	ds_read_b32 v95, v163 offset:39584
	v_pk_mul_f32 v[148:149], v[24:25], v[40:41] op_sel_hi:[1,0]
	v_pk_mul_f32 v[150:151], v[26:27], v[40:41] op_sel_hi:[1,0]
	v_add_f32_e32 v168, v96, v97
	v_add_f32_e32 v166, v98, v99
	v_add_f32_e32 v169, v100, v101
	v_add_f32_e32 v170, v172, v173
	v_pk_fma_f32 v[148:149], v[32:33], v[40:41], v[148:149] op_sel:[0,1,0] op_sel_hi:[1,1,1]
	v_pk_fma_f32 v[150:151], v[34:35], v[40:41], v[150:151] op_sel:[0,1,0] op_sel_hi:[1,1,1]
	v_add_f32_dpp v168, v168, v168 row_mirror row_mask:0xf bank_mask:0xf bound_ctrl:1
	v_add_f32_dpp v166, v166, v166 row_mirror row_mask:0xf bank_mask:0xf bound_ctrl:1
	v_add_f32_dpp v169, v169, v169 row_mirror row_mask:0xf bank_mask:0xf bound_ctrl:1
	v_add_f32_dpp v170, v170, v170 row_mirror row_mask:0xf bank_mask:0xf bound_ctrl:1
	v_add_f32_dpp v168, v168, v168 row_half_mirror row_mask:0xf bank_mask:0xf bound_ctrl:1
	v_add_f32_dpp v166, v166, v166 row_half_mirror row_mask:0xf bank_mask:0xf bound_ctrl:1
	v_add_f32_dpp v169, v169, v169 row_half_mirror row_mask:0xf bank_mask:0xf bound_ctrl:1
	v_add_f32_dpp v170, v170, v170 row_half_mirror row_mask:0xf bank_mask:0xf bound_ctrl:1
	v_add_f32_dpp v168, v168, v168 quad_perm:[1,0,3,2] row_mask:0xf bank_mask:0xf bound_ctrl:1
	v_add_f32_dpp v166, v166, v166 quad_perm:[1,0,3,2] row_mask:0xf bank_mask:0xf bound_ctrl:1
	v_add_f32_dpp v169, v169, v169 quad_perm:[1,0,3,2] row_mask:0xf bank_mask:0xf bound_ctrl:1
	v_add_f32_dpp v170, v170, v170 quad_perm:[1,0,3,2] row_mask:0xf bank_mask:0xf bound_ctrl:1
	v_add_f32_dpp v168, v168, v168 quad_perm:[2,3,0,1] row_mask:0xf bank_mask:0xf bound_ctrl:1
	v_add_f32_dpp v166, v166, v166 quad_perm:[2,3,0,1] row_mask:0xf bank_mask:0xf bound_ctrl:1
	v_add_f32_dpp v169, v169, v169 quad_perm:[2,3,0,1] row_mask:0xf bank_mask:0xf bound_ctrl:1
	v_add_f32_dpp v170, v170, v170 quad_perm:[2,3,0,1] row_mask:0xf bank_mask:0xf bound_ctrl:1
	v_fma_f32 v164, v40, v37, v169
	v_fma_f32 v171, v40, v39, v170
	v_pk_fma_f32 v[148:149], v[20:21], v[166:167], v[148:149] op_sel_hi:[1,0,1]
	v_fma_f32 v167, v166, v36, v164
	v_pk_fma_f32 v[150:151], v[22:23], v[166:167], v[150:151] op_sel_hi:[1,0,1]
	v_fma_f32 v171, v166, v38, v171
	v_cndmask_b32_e64 v162, v162, v168, s[60:61]
	v_pk_fma_f32 v[148:149], v[28:29], v[166:167], v[148:149] op_sel:[0,1,0] op_sel_hi:[1,1,1]
	v_pk_fma_f32 v[150:151], v[30:31], v[166:167], v[150:151] op_sel:[0,1,0] op_sel_hi:[1,1,1]
	v_cndmask_b32_e64 v162, v162, v171, s[62:63]
	v_pk_fma_f32 v[144:145], v[144:145], v[16:17], v[148:149]
	v_pk_fma_f32 v[146:147], v[146:147], v[18:19], v[150:151]
	s_waitcnt lgkmcnt(0)
	v_pk_mul_f32 v[96:97], v[144:145], v[12:13]
	v_pk_mul_f32 v[98:99], v[144:145], v[54:55]
	v_pk_mul_f32 v[100:101], v[144:145], v[58:59]
	v_pk_mul_f32 v[172:173], v[144:145], v[62:63]
	v_pk_fma_f32 v[96:97], v[146:147], v[14:15], v[96:97]
	v_pk_fma_f32 v[98:99], v[146:147], v[56:57], v[98:99]
	v_pk_fma_f32 v[100:101], v[146:147], v[60:61], v[100:101]
	v_pk_fma_f32 v[172:173], v[146:147], v[64:65], v[172:173]
	ds_read_b128 v[0:3], v174 offset:39872
	ds_read_b128 v[4:7], v174 offset:40128
	ds_read_b128 v[8:11], v174 offset:40384
	ds_read_b128 v[12:15], v174 offset:40640
	ds_read_b128 v[16:19], v174 offset:40896
	ds_read_b128 v[20:23], v174 offset:41152
	ds_read_b128 v[24:27], v174 offset:41408
	ds_read_b128 v[28:31], v174 offset:41664
	ds_read_b128 v[32:35], v174 offset:41920
	ds_read_b128 v[36:39], v175 offset:42688
	ds_read_b32 v40, v163 offset:42176
	ds_read_b32 v41, v163 offset:42432
	v_pk_mul_f32 v[148:149], v[78:79], v[94:95] op_sel_hi:[1,0]
	v_pk_mul_f32 v[150:151], v[80:81], v[94:95] op_sel_hi:[1,0]
	v_add_f32_e32 v168, v96, v97
	v_add_f32_e32 v166, v98, v99
	v_add_f32_e32 v169, v100, v101
	v_add_f32_e32 v170, v172, v173
	v_pk_fma_f32 v[148:149], v[86:87], v[94:95], v[148:149] op_sel:[0,1,0] op_sel_hi:[1,1,1]
	v_pk_fma_f32 v[150:151], v[88:89], v[94:95], v[150:151] op_sel:[0,1,0] op_sel_hi:[1,1,1]
	v_add_f32_dpp v168, v168, v168 row_mirror row_mask:0xf bank_mask:0xf bound_ctrl:1
	v_add_f32_dpp v166, v166, v166 row_mirror row_mask:0xf bank_mask:0xf bound_ctrl:1
	v_add_f32_dpp v169, v169, v169 row_mirror row_mask:0xf bank_mask:0xf bound_ctrl:1
	v_add_f32_dpp v170, v170, v170 row_mirror row_mask:0xf bank_mask:0xf bound_ctrl:1
	v_add_f32_dpp v168, v168, v168 row_half_mirror row_mask:0xf bank_mask:0xf bound_ctrl:1
	v_add_f32_dpp v166, v166, v166 row_half_mirror row_mask:0xf bank_mask:0xf bound_ctrl:1
	v_add_f32_dpp v169, v169, v169 row_half_mirror row_mask:0xf bank_mask:0xf bound_ctrl:1
	v_add_f32_dpp v170, v170, v170 row_half_mirror row_mask:0xf bank_mask:0xf bound_ctrl:1
	v_add_f32_dpp v168, v168, v168 quad_perm:[1,0,3,2] row_mask:0xf bank_mask:0xf bound_ctrl:1
	v_add_f32_dpp v166, v166, v166 quad_perm:[1,0,3,2] row_mask:0xf bank_mask:0xf bound_ctrl:1
	v_add_f32_dpp v169, v169, v169 quad_perm:[1,0,3,2] row_mask:0xf bank_mask:0xf bound_ctrl:1
	v_add_f32_dpp v170, v170, v170 quad_perm:[1,0,3,2] row_mask:0xf bank_mask:0xf bound_ctrl:1
	v_add_f32_dpp v168, v168, v168 quad_perm:[2,3,0,1] row_mask:0xf bank_mask:0xf bound_ctrl:1
	v_add_f32_dpp v166, v166, v166 quad_perm:[2,3,0,1] row_mask:0xf bank_mask:0xf bound_ctrl:1
	v_add_f32_dpp v169, v169, v169 quad_perm:[2,3,0,1] row_mask:0xf bank_mask:0xf bound_ctrl:1
	v_add_f32_dpp v170, v170, v170 quad_perm:[2,3,0,1] row_mask:0xf bank_mask:0xf bound_ctrl:1
	v_fma_f32 v164, v94, v91, v169
	v_fma_f32 v171, v94, v93, v170
	v_pk_fma_f32 v[148:149], v[74:75], v[166:167], v[148:149] op_sel_hi:[1,0,1]
	v_fma_f32 v167, v166, v90, v164
	v_pk_fma_f32 v[150:151], v[76:77], v[166:167], v[150:151] op_sel_hi:[1,0,1]
	v_fma_f32 v171, v166, v92, v171
	v_cndmask_b32_e64 v162, v162, v168, s[64:65]
	v_pk_fma_f32 v[148:149], v[82:83], v[166:167], v[148:149] op_sel:[0,1,0] op_sel_hi:[1,1,1]
	v_pk_fma_f32 v[150:151], v[84:85], v[166:167], v[150:151] op_sel:[0,1,0] op_sel_hi:[1,1,1]
	v_cndmask_b32_e64 v162, v162, v171, s[66:67]
	v_pk_fma_f32 v[144:145], v[144:145], v[70:71], v[148:149]
	v_pk_fma_f32 v[146:147], v[146:147], v[72:73], v[150:151]
	s_waitcnt lgkmcnt(0)
	v_pk_mul_f32 v[96:97], v[144:145], v[66:67]
	v_pk_mul_f32 v[98:99], v[144:145], v[0:1]
	v_pk_mul_f32 v[100:101], v[144:145], v[4:5]
	v_pk_mul_f32 v[172:173], v[144:145], v[8:9]
	v_pk_fma_f32 v[96:97], v[146:147], v[68:69], v[96:97]
	v_pk_fma_f32 v[98:99], v[146:147], v[2:3], v[98:99]
	v_pk_fma_f32 v[100:101], v[146:147], v[6:7], v[100:101]
	v_pk_fma_f32 v[172:173], v[146:147], v[10:11], v[172:173]
	ds_read_b128 v[54:57], v174 offset:42720
	ds_read_b128 v[58:61], v174 offset:42976
	ds_read_b128 v[62:65], v174 offset:43232
	ds_read_b128 v[66:69], v174 offset:43488
	ds_read_b128 v[70:73], v174 offset:43744
	ds_read_b128 v[74:77], v174 offset:44000
	ds_read_b128 v[78:81], v174 offset:44256
	ds_read_b128 v[82:85], v174 offset:44512
	ds_read_b128 v[86:89], v174 offset:44768
	ds_read_b128 v[90:93], v175 offset:45536
	ds_read_b32 v94, v163 offset:45024
	ds_read_b32 v95, v163 offset:45280
	v_pk_mul_f32 v[148:149], v[24:25], v[40:41] op_sel_hi:[1,0]
	v_pk_mul_f32 v[150:151], v[26:27], v[40:41] op_sel_hi:[1,0]
	v_add_f32_e32 v168, v96, v97
	v_add_f32_e32 v166, v98, v99
	v_add_f32_e32 v169, v100, v101
	v_add_f32_e32 v170, v172, v173
	v_pk_fma_f32 v[148:149], v[32:33], v[40:41], v[148:149] op_sel:[0,1,0] op_sel_hi:[1,1,1]
	v_pk_fma_f32 v[150:151], v[34:35], v[40:41], v[150:151] op_sel:[0,1,0] op_sel_hi:[1,1,1]
	v_add_f32_dpp v168, v168, v168 row_mirror row_mask:0xf bank_mask:0xf bound_ctrl:1
	v_add_f32_dpp v166, v166, v166 row_mirror row_mask:0xf bank_mask:0xf bound_ctrl:1
	v_add_f32_dpp v169, v169, v169 row_mirror row_mask:0xf bank_mask:0xf bound_ctrl:1
	v_add_f32_dpp v170, v170, v170 row_mirror row_mask:0xf bank_mask:0xf bound_ctrl:1
	v_add_f32_dpp v168, v168, v168 row_half_mirror row_mask:0xf bank_mask:0xf bound_ctrl:1
	v_add_f32_dpp v166, v166, v166 row_half_mirror row_mask:0xf bank_mask:0xf bound_ctrl:1
	v_add_f32_dpp v169, v169, v169 row_half_mirror row_mask:0xf bank_mask:0xf bound_ctrl:1
	v_add_f32_dpp v170, v170, v170 row_half_mirror row_mask:0xf bank_mask:0xf bound_ctrl:1
	v_add_f32_dpp v168, v168, v168 quad_perm:[1,0,3,2] row_mask:0xf bank_mask:0xf bound_ctrl:1
	v_add_f32_dpp v166, v166, v166 quad_perm:[1,0,3,2] row_mask:0xf bank_mask:0xf bound_ctrl:1
	v_add_f32_dpp v169, v169, v169 quad_perm:[1,0,3,2] row_mask:0xf bank_mask:0xf bound_ctrl:1
	v_add_f32_dpp v170, v170, v170 quad_perm:[1,0,3,2] row_mask:0xf bank_mask:0xf bound_ctrl:1
	v_add_f32_dpp v168, v168, v168 quad_perm:[2,3,0,1] row_mask:0xf bank_mask:0xf bound_ctrl:1
	v_add_f32_dpp v166, v166, v166 quad_perm:[2,3,0,1] row_mask:0xf bank_mask:0xf bound_ctrl:1
	v_add_f32_dpp v169, v169, v169 quad_perm:[2,3,0,1] row_mask:0xf bank_mask:0xf bound_ctrl:1
	v_add_f32_dpp v170, v170, v170 quad_perm:[2,3,0,1] row_mask:0xf bank_mask:0xf bound_ctrl:1
	v_fma_f32 v164, v40, v37, v169
	v_fma_f32 v171, v40, v39, v170
	v_pk_fma_f32 v[148:149], v[20:21], v[166:167], v[148:149] op_sel_hi:[1,0,1]
	v_fma_f32 v167, v166, v36, v164
	v_pk_fma_f32 v[150:151], v[22:23], v[166:167], v[150:151] op_sel_hi:[1,0,1]
	v_fma_f32 v171, v166, v38, v171
	v_cndmask_b32_e64 v162, v162, v168, s[68:69]
	v_pk_fma_f32 v[148:149], v[28:29], v[166:167], v[148:149] op_sel:[0,1,0] op_sel_hi:[1,1,1]
	v_pk_fma_f32 v[150:151], v[30:31], v[166:167], v[150:151] op_sel:[0,1,0] op_sel_hi:[1,1,1]
	v_cndmask_b32_e64 v162, v162, v171, s[70:71]
	v_pk_fma_f32 v[144:145], v[144:145], v[16:17], v[148:149]
	v_pk_fma_f32 v[146:147], v[146:147], v[18:19], v[150:151]
	s_waitcnt lgkmcnt(0)
	v_pk_mul_f32 v[96:97], v[144:145], v[12:13]
	v_pk_mul_f32 v[98:99], v[144:145], v[54:55]
	v_pk_mul_f32 v[100:101], v[144:145], v[58:59]
	v_pk_mul_f32 v[172:173], v[144:145], v[62:63]
	v_pk_fma_f32 v[96:97], v[146:147], v[14:15], v[96:97]
	v_pk_fma_f32 v[98:99], v[146:147], v[56:57], v[98:99]
	v_pk_fma_f32 v[100:101], v[146:147], v[60:61], v[100:101]
	v_pk_fma_f32 v[172:173], v[146:147], v[64:65], v[172:173]
	v_pk_mul_f32 v[148:149], v[78:79], v[94:95] op_sel_hi:[1,0]
	v_pk_mul_f32 v[150:151], v[80:81], v[94:95] op_sel_hi:[1,0]
	v_add_f32_e32 v168, v96, v97
	v_add_f32_e32 v166, v98, v99
	v_add_f32_e32 v169, v100, v101
	v_add_f32_e32 v170, v172, v173
	v_pk_fma_f32 v[148:149], v[86:87], v[94:95], v[148:149] op_sel:[0,1,0] op_sel_hi:[1,1,1]
	v_pk_fma_f32 v[150:151], v[88:89], v[94:95], v[150:151] op_sel:[0,1,0] op_sel_hi:[1,1,1]
	v_add_f32_dpp v168, v168, v168 row_mirror row_mask:0xf bank_mask:0xf bound_ctrl:1
	v_add_f32_dpp v166, v166, v166 row_mirror row_mask:0xf bank_mask:0xf bound_ctrl:1
	v_add_f32_dpp v169, v169, v169 row_mirror row_mask:0xf bank_mask:0xf bound_ctrl:1
	v_add_f32_dpp v170, v170, v170 row_mirror row_mask:0xf bank_mask:0xf bound_ctrl:1
	v_add_f32_dpp v168, v168, v168 row_half_mirror row_mask:0xf bank_mask:0xf bound_ctrl:1
	v_add_f32_dpp v166, v166, v166 row_half_mirror row_mask:0xf bank_mask:0xf bound_ctrl:1
	v_add_f32_dpp v169, v169, v169 row_half_mirror row_mask:0xf bank_mask:0xf bound_ctrl:1
	v_add_f32_dpp v170, v170, v170 row_half_mirror row_mask:0xf bank_mask:0xf bound_ctrl:1
	v_add_f32_dpp v168, v168, v168 quad_perm:[1,0,3,2] row_mask:0xf bank_mask:0xf bound_ctrl:1
	v_add_f32_dpp v166, v166, v166 quad_perm:[1,0,3,2] row_mask:0xf bank_mask:0xf bound_ctrl:1
	v_add_f32_dpp v169, v169, v169 quad_perm:[1,0,3,2] row_mask:0xf bank_mask:0xf bound_ctrl:1
	v_add_f32_dpp v170, v170, v170 quad_perm:[1,0,3,2] row_mask:0xf bank_mask:0xf bound_ctrl:1
	v_add_f32_dpp v168, v168, v168 quad_perm:[2,3,0,1] row_mask:0xf bank_mask:0xf bound_ctrl:1
	v_add_f32_dpp v166, v166, v166 quad_perm:[2,3,0,1] row_mask:0xf bank_mask:0xf bound_ctrl:1
	v_add_f32_dpp v169, v169, v169 quad_perm:[2,3,0,1] row_mask:0xf bank_mask:0xf bound_ctrl:1
	v_add_f32_dpp v170, v170, v170 quad_perm:[2,3,0,1] row_mask:0xf bank_mask:0xf bound_ctrl:1
	v_fma_f32 v164, v94, v91, v169
	v_fma_f32 v171, v94, v93, v170
	v_pk_fma_f32 v[148:149], v[74:75], v[166:167], v[148:149] op_sel_hi:[1,0,1]
	v_fma_f32 v167, v166, v90, v164
	v_pk_fma_f32 v[150:151], v[76:77], v[166:167], v[150:151] op_sel_hi:[1,0,1]
	v_fma_f32 v171, v166, v92, v171
	v_cndmask_b32_e64 v162, v162, v168, s[44:45]
	v_pk_fma_f32 v[148:149], v[82:83], v[166:167], v[148:149] op_sel:[0,1,0] op_sel_hi:[1,1,1]
	v_pk_fma_f32 v[150:151], v[84:85], v[166:167], v[150:151] op_sel:[0,1,0] op_sel_hi:[1,1,1]
	v_cndmask_b32_e64 v162, v162, v171, s[42:43]
	v_pk_fma_f32 v[144:145], v[144:145], v[70:71], v[148:149]
	v_pk_fma_f32 v[146:147], v[146:147], v[72:73], v[150:151]
	v_mov_b64_e32 v[24:25], v[66:67]
	v_mov_b64_e32 v[26:27], v[68:69]
	s_mov_b64 s[92:93], 0
	s_setprio 0
